# states tile entry: the workgroup barrier is placed after the dt / dt_bias / A_log loads are issued instead of before them
# baseline (speedup 1.0000x reference)
.LBB0_1272:
	v_mov_b32_e32 v121, v252
	s_waitcnt vmcnt(63) expcnt(7) lgkmcnt(15)
	s_load_dwordx2 s[4:5], s[0:1], 0x60
	s_load_dwordx2 s[98:99], s[0:1], 0x68
	s_add_i32 s9, s18, 0xfffffdd9
	v_readfirstlane_b32 s8, v121
	v_and_b32_e32 v140, 63, v121
	s_ashr_i32 s30, s8, 6
	s_lshl_b32 s10, s9, 6
	v_or_b32_e32 v0, s10, v140
	s_ashr_i32 s31, s30, 31
	v_lshlrev_b64 v[2:3], 5, v[0:1]
	s_lshl_b64 s[2:3], s[30:31], 2
	v_lshl_add_u64 v[2:3], s[12:13], 0, v[2:3]
	s_waitcnt lgkmcnt(0)
	s_add_u32 s4, s4, s2
	v_lshl_add_u64 v[2:3], v[2:3], 0, s[2:3]
	s_addc_u32 s5, s5, s3
	global_load_dword v0, v[2:3], off
	s_nop 0
	global_load_dword v2, v1, s[4:5]
	s_add_u32 s98, s98, s2
	s_addc_u32 s99, s99, s3
	global_load_dword v250, v1, s[98:99]
	s_barrier
	s_mov_b32 s4, 0x41a00000
	s_waitcnt vmcnt(0)
	v_add_f32_e32 v0, v0, v2
	v_cmp_nlt_f32_e32 vcc, s4, v0
	s_and_saveexec_b64 s[4:5], vcc
	s_cbranch_execz .LBB0_1274
	v_mul_f32_e32 v2, 0x3fb8aa3b, v0
	v_rndne_f32_e32 v3, v2
	s_mov_b32 s6, 0x3fb8aa3b
	v_sub_f32_e32 v4, v2, v3
	v_fma_f32 v2, v0, s6, -v2
	v_fmac_f32_e32 v2, 0x32a5705f, v0
	v_add_f32_e32 v2, v4, v2
	v_cvt_i32_f32_e32 v3, v3
	v_exp_f32_e32 v2, v2
	s_mov_b32 s6, 0xc2ce8ed0
	v_cmp_ngt_f32_e32 vcc, s6, v0
	s_mov_b32 s6, 0x3f2aaaab
	v_ldexp_f32 v2, v2, v3
	v_cndmask_b32_e32 v2, 0, v2, vcc
	v_cmp_nlt_f32_e32 vcc, s80, v0
	s_nop 1
	v_cndmask_b32_e32 v0, v183, v2, vcc
	v_add_f32_e32 v4, 1.0, v0
	v_add_f32_e32 v2, -1.0, v4
	v_sub_f32_e32 v3, v2, v4
	v_add_f32_e32 v3, 1.0, v3
	v_sub_f32_e32 v2, v0, v2
	v_add_f32_e32 v5, v2, v3
	v_frexp_mant_f32_e32 v6, v4
	v_cvt_f64_f32_e32 v[2:3], v4
	v_frexp_exp_i32_f64_e32 v2, v[2:3]
	v_cmp_gt_f32_e32 vcc, s6, v6
	s_mov_b32 s6, 0x3f317218
	s_nop 0
	v_subbrev_co_u32_e32 v10, vcc, 0, v2, vcc
	v_sub_u32_e32 v2, 0, v10
	v_ldexp_f32 v3, v4, v2
	v_add_f32_e32 v4, -1.0, v3
	v_add_f32_e32 v6, 1.0, v3
	v_ldexp_f32 v2, v5, v2
	v_add_f32_e32 v5, 1.0, v4
	v_add_f32_e32 v7, -1.0, v6
	v_sub_f32_e32 v5, v3, v5
	v_sub_f32_e32 v3, v3, v7
	v_add_f32_e32 v5, v2, v5
	v_add_f32_e32 v2, v2, v3
	v_add_f32_e32 v11, v6, v2
	v_rcp_f32_e32 v13, v11
	v_sub_f32_e32 v3, v6, v11
	v_add_f32_e32 v12, v2, v3
	v_add_f32_e32 v3, v4, v5
	v_mul_f32_e32 v15, v3, v13
	v_sub_f32_e32 v2, v4, v3
	v_mul_f32_e32 v4, v11, v15
	v_fma_f32 v6, v15, v11, -v4
	v_fmac_f32_e32 v6, v15, v12
	v_add_f32_e32 v14, v5, v2
	v_add_f32_e32 v2, v4, v6
	v_sub_f32_e32 v5, v3, v2
	v_pk_add_f32 v[8:9], v[2:3], v[4:5] neg_lo:[0,1] neg_hi:[0,1]
	v_mov_b32_e32 v7, v2
	v_pk_add_f32 v[2:3], v[8:9], v[6:7] neg_lo:[0,1] neg_hi:[0,1]
	s_nop 0
	v_add_f32_e32 v3, v14, v3
	v_add_f32_e32 v2, v2, v3
	v_add_f32_e32 v3, v5, v2
	v_mul_f32_e32 v14, v13, v3
	v_mul_f32_e32 v4, v11, v14
	v_fma_f32 v6, v14, v11, -v4
	v_fmac_f32_e32 v6, v14, v12
	v_sub_f32_e32 v5, v5, v3
	v_add_f32_e32 v11, v2, v5
	v_add_f32_e32 v2, v4, v6
	v_sub_f32_e32 v5, v3, v2
	v_pk_add_f32 v[8:9], v[2:3], v[4:5] neg_lo:[0,1] neg_hi:[0,1]
	v_mov_b32_e32 v7, v2
	v_pk_add_f32 v[2:3], v[8:9], v[6:7] neg_lo:[0,1] neg_hi:[0,1]
	s_nop 0
	v_add_f32_e32 v3, v11, v3
	v_add_f32_e32 v2, v2, v3
	v_add_f32_e32 v3, v15, v14
	v_add_f32_e32 v2, v5, v2
	v_sub_f32_e32 v4, v3, v15
	v_mul_f32_e32 v2, v13, v2
	v_sub_f32_e32 v4, v14, v4
	v_add_f32_e32 v4, v4, v2
	v_add_f32_e32 v6, v3, v4
	v_mul_f32_e32 v7, v6, v6
	v_fmamk_f32 v2, v7, 0x3e9b6dac, v178
	v_fmaak_f32 v165, v7, v2, 0x3f2aaada
	v_cvt_f32_i32_e32 v2, v10
	v_sub_f32_e32 v3, v6, v3
	v_sub_f32_e32 v3, v4, v3
	v_ldexp_f32 v8, v3, 1
	v_mul_f32_e32 v3, v6, v7
	v_ldexp_f32 v5, v6, 1
	v_pk_mul_f32 v[6:7], v[2:3], v[164:165]
	s_nop 0
	v_fma_f32 v4, v2, s6, -v6
	v_fmac_f32_e32 v4, 0xb102e308, v2
	v_pk_add_f32 v[2:3], v[6:7], v[4:5]
	s_mov_b32 s6, 0x7f800000
	v_sub_f32_e32 v5, v3, v5
	v_sub_f32_e32 v5, v7, v5
	v_add_f32_e32 v9, v8, v5
	v_mov_b32_e32 v8, v6
	v_pk_add_f32 v[6:7], v[2:3], v[6:7] neg_lo:[0,1] neg_hi:[0,1]
	v_pk_add_f32 v[10:11], v[2:3], v[8:9]
	v_mov_b32_e32 v5, v2
	v_mov_b32_e32 v7, v11
	v_pk_add_f32 v[12:13], v[4:5], v[6:7] neg_lo:[0,1] neg_hi:[0,1]
	v_pk_add_f32 v[4:5], v[4:5], v[6:7]
	v_mov_b32_e32 v8, v9
	v_pk_add_f32 v[6:7], v[4:5], v[2:3] op_sel:[1,0] op_sel_hi:[0,1] neg_lo:[0,1] neg_hi:[0,1]
	v_pk_add_f32 v[14:15], v[10:11], v[6:7] op_sel_hi:[1,0] neg_lo:[0,1] neg_hi:[0,1]
	v_mov_b32_e32 v10, v11
	v_mov_b32_e32 v11, v5
	v_pk_mov_b32 v[6:7], v[2:3], v[6:7] op_sel:[1,0]
	v_mov_b32_e32 v9, v2
	v_pk_add_f32 v[6:7], v[10:11], v[6:7] neg_lo:[0,1] neg_hi:[0,1]
	v_mov_b32_e32 v14, v12
	v_pk_add_f32 v[2:3], v[8:9], v[6:7] neg_lo:[0,1] neg_hi:[0,1]
	v_mov_b32_e32 v13, v5
	v_pk_add_f32 v[6:7], v[14:15], v[2:3]
	v_cmp_neq_f32_e32 vcc, s6, v0
	v_pk_add_f32 v[8:9], v[6:7], v[6:7] op_sel:[0,1] op_sel_hi:[1,0]
	s_mov_b32 s6, 0x33800000
	v_pk_add_f32 v[4:5], v[4:5], v[8:9] op_sel:[1,0] op_sel_hi:[0,1]
	v_mov_b32_e32 v7, v4
	v_pk_add_f32 v[10:11], v[6:7], v[12:13] neg_lo:[0,1] neg_hi:[0,1]
	v_mov_b32_e32 v3, v8
	v_sub_f32_e32 v5, v6, v10
	v_pk_add_f32 v[2:3], v[2:3], v[10:11] neg_lo:[0,1] neg_hi:[0,1]
	v_sub_f32_e32 v5, v12, v5
	v_add_f32_e32 v2, v2, v5
	v_add_f32_e32 v2, v2, v3
	v_add_f32_e32 v2, v4, v2
	v_cndmask_b32_e32 v2, v183, v2, vcc
	v_cmp_lt_f32_e64 vcc, |v0|, s6
	s_nop 1
	v_cndmask_b32_e32 v0, v2, v0, vcc
